# first-tile dependency waits in mlp1 and in-proj: only wave 0 polls, the other waves wait at a workgroup barrier
# baseline (speedup 1.0000x reference)
.Lm1_cont:
.LBB0_81:
	s_mul_hi_i32 s6, s49, 0x2aaaaaab
	s_lshr_b32 s14, s6, 31
	s_ashr_i32 s6, s6, 2
	s_add_i32 s6, s6, s14
	s_mul_i32 s14, s6, 24
	s_sub_i32 s14, s49, s14
	s_lshl_b32 s26, s14, 8
	s_lshl_b32 s22, s6, 7
	s_ashr_i32 s27, s26, 31
	s_ashr_i32 s23, s22, 31
	s_lshl_b64 s[34:35], s[26:27], 11
	s_lshl_b64 s[36:37], s[22:23], 11
	s_and_b64 vcc, exec, s[38:39]
	s_cbranch_vccnz .Lrelu2_pf
	v_readfirstlane_b32 s52, v137
	s_cmp_lt_u32 s52, 64
	s_cbranch_scc0 .Lm1ok_a
	v_readlane_b32 s52, v255, 40
	s_add_i32 s52, s52, 0x5d0e1000
	s_lshl_b32 s53, s14, 7
	s_add_u32 s64, s94, 0xcbc8000
	s_addc_u32 s65, s95, 0
	v_and_b32_e32 v226, 7, v137
	v_lshlrev_b32_e32 v226, 4, v226
	v_add_u32_e32 v226, s53, v226
	s_mov_b32 s53, 0x100000

.Lm1ok_a:
	s_barrier
	s_mov_b32 m0, s8
	v_lshl_add_u64 v[2:3], v[102:103], 0, s[34:35]
	global_load_lds_dwordx4 v[2:3], off sc1
	v_lshl_add_u64 v[6:7], v[2:3], 0, s[30:31]
	s_mov_b32 m0, s11
	s_mov_b64 s[16:17], 0xc000
	global_load_lds_dwordx4 v[6:7], off sc1
	v_lshl_add_u64 v[6:7], v[2:3], 0, s[24:25]
	s_add_i32 m0, s8, 0x800
	v_lshl_add_u64 v[4:5], v[106:107], 0, s[36:37]
	global_load_lds_dwordx4 v[6:7], off sc1
	v_lshl_add_u64 v[6:7], v[2:3], 0, s[16:17]
	s_mov_b32 m0, s12
	s_mov_b64 s[16:17], 0x4080
	global_load_lds_dwordx4 v[6:7], off sc1
	s_mov_b32 m0, s13
	v_lshl_add_u64 v[6:7], v[4:5], 0, s[30:31]
	global_load_lds_dwordx4 v[4:5], off sc1
	s_mov_b32 m0, s40
	s_mov_b64 s[38:39], 0x8080
	global_load_lds_dwordx4 v[6:7], off sc1
	v_lshl_add_u64 v[6:7], v[2:3], 0, s[2:3]
	s_add_i32 m0, s8, 0xc000
	s_mov_b64 s[50:51], 0x8100
	global_load_lds_dwordx4 v[6:7], off sc1
	v_lshl_add_u64 v[6:7], v[2:3], 0, s[16:17]
	s_mov_b32 m0, s41
	s_nop 0
	global_load_lds_dwordx4 v[6:7], off sc1
	v_lshl_add_u64 v[6:7], v[2:3], 0, s[38:39]
	s_mov_b32 m0, s42
	s_mov_b64 s[38:39], 0xc080
	global_load_lds_dwordx4 v[6:7], off sc1
	v_lshl_add_u64 v[6:7], v[2:3], 0, s[38:39]
	s_mov_b32 m0, s43
	s_mov_b64 s[38:39], 0x4100
	global_load_lds_dwordx4 v[6:7], off sc1
	v_lshl_add_u64 v[6:7], v[4:5], 0, s[2:3]
	s_add_i32 m0, s9, 0x14000
	s_nop 0
	global_load_lds_dwordx4 v[6:7], off sc1
	v_lshl_add_u64 v[6:7], v[4:5], 0, s[16:17]
	s_mov_b32 m0, s44
	s_mov_b64 s[16:17], 0x100
	global_load_lds_dwordx4 v[6:7], off sc1
	v_lshl_add_u64 v[6:7], v[2:3], 0, s[16:17]
	s_add_i32 m0, s8, 0x18000
	s_nop 0
	global_load_lds_dwordx4 v[6:7], off sc1
	v_lshl_add_u64 v[6:7], v[2:3], 0, s[38:39]
	s_mov_b32 m0, s45
	s_nop 0
	global_load_lds_dwordx4 v[6:7], off sc1
	v_lshl_add_u64 v[6:7], v[2:3], 0, s[50:51]
	s_mov_b32 m0, s46
	s_mov_b64 s[50:51], 0xc100
	global_load_lds_dwordx4 v[6:7], off sc1
	v_lshl_add_u64 v[2:3], v[2:3], 0, s[50:51]
	s_mov_b32 m0, s47
	s_nop 0
	global_load_lds_dwordx4 v[2:3], off sc1
	v_lshl_add_u64 v[2:3], v[4:5], 0, s[16:17]
	s_add_i32 m0, s9, 0x20000
	s_nop 0
	global_load_lds_dwordx4 v[2:3], off sc1
	v_lshl_add_u64 v[2:3], v[4:5], 0, s[38:39]
	s_mov_b32 m0, s48
	s_nop 0
	global_load_lds_dwordx4 v[2:3], off sc1
	s_branch .LBB0_83

.Lip_block:
	s_cmp_lg_u32 s66, 0
	s_cbranch_scc1 .Lip_noconvpf
	v_readfirstlane_b32 s65, v137
	s_cmp_lt_u32 s65, 64
	s_cbranch_scc0 .Lip_first_wait
	s_add_u32 s46, s94, 0xcbcd000
	s_addc_u32 s47, s95, 0
	v_and_b32_e32 v67, 63, v137
	v_lshlrev_b32_e32 v67, 4, v67
	global_load_dwordx4 v[72:75], v67, s[46:47] sc1

.Lip_cok:
.Lip_first_wait:
	s_barrier
	s_mov_b32 s66, 1
